# compressed-branch NSA loop: last QK MFMA of the fused path writes the score tile straight into the pending registers (end-of-step copy and its wait on the MFMA chain removed), on top of the combined v
# baseline (speedup 1.0000x reference)
; #define LAS __attribute__((address_space(3)))
; DI float xh_max(float x) { const unsigned u = __float_as_uint(x); const auto r = __builtin_amdgcn_permlane32_swap(u, u, false, false); return fmaxf(__uint_as_float(r[0]), __uint_as_float(r[1])); }
; #define MFMA32(a, b, c) __builtin_amdgcn_mfma_f32_32x32x16_bf16((a), (b), (c), 0, 0, 0)
; DI f32x16 co_qk1(LAS unsigned char* st, const bf16x8 (&qf)[8], int ka_in) {
;     const int ka = ka_in;
;     f32x16 S;
; #pragma unroll
;     for (int i = 0; i < 16; ++i) S[i] = 0.f;
;     __builtin_amdgcn_s_setprio(1);
; #pragma unroll
;     for (int ks = 0; ks < 8; ++ks) { const bf16x8 a = *(const LAS bf16x8*)(st + (ka ^ (32 * ks))); S = MFMA32(a, qf[ks], S); }
;     __builtin_amdgcn_s_setprio(0);
;     return S;
; }
; template <int MODE>
; DI void co_finish(f32x16 S, LAS unsigned char* st, int key_base, AttnState& as, int tq, bool rowsel, int vb_in, int hh) {
;     const int vb = vb_in;
;     {
;         const int base = key_base + 4 * hh;
;         const int hi = (MODE == 0) ? (((tq - 31) >> 4) - base) : (tq - base);
;         const int lo = hi - 512;
; #pragma unroll
;         for (int i = 0; i < 16; ++i) { const int c = (i & 3) + 8 * (i >> 2); bool ok = (c <= hi); if (MODE == 2) ok = ok && (c > lo); if (MODE == 1) ok = ok && rowsel; S[i] = ok ? S[i] : -1e30f; }
;     }
;     float mx = S[0];
; #pragma unroll
;     for (int i = 1; i < 16; ++i) mx = fmaxf(mx, S[i]);
;     mx = xh_max(mx);
;     const float mxs = mx * SM_SCALE; const bool need = mxs > as.m + 8.f;
;     const float mnew = need ? mxs : as.m, muse = -fmaxf(mnew, -1e20f); float ps = 0.f;
; #pragma unroll
;     for (int i = 0; i < 16; ++i) { const float p = __builtin_amdgcn_exp2f(__builtin_fmaf(S[i], SM_SCALE, muse)); S[i] = p; ps += p; }
.Lfs_cmp:
	v_add_u32_e32 v246, s16, v162
	ds_read_b128 v[238:241], v246
	v_add_u32_e32 v246, s16, v164
	ds_read_b128 v[242:245], v246
	v_add_u32_e32 v0, s80, v180
	v_cmp_lt_i32_e32 vcc, -1, v0
	s_nop 1
	v_cndmask_b32_e32 v3, v153, v16, vcc
	v_cmp_lt_i32_e32 vcc, 0, v0
	v_max_f32_e32 v2, v3, v3
	s_nop 0
	v_cndmask_b32_e32 v4, v153, v17, vcc
	v_cmp_lt_i32_e32 vcc, 1, v0
	s_nop 1
	v_cndmask_b32_e32 v5, v153, v18, vcc
	v_cmp_lt_i32_e32 vcc, 2, v0
	s_waitcnt lgkmcnt(1)
	v_mfma_f32_32x32x16_bf16 v[96:111], v[238:241], v[112:115], 0
	v_add_u32_e32 v246, s16, v165
	ds_read_b128 v[238:241], v246
	s_nop 1
	v_cndmask_b32_e32 v6, v153, v19, vcc
	v_cmp_lt_i32_e32 vcc, 7, v0
	s_nop 1
	v_cndmask_b32_e32 v7, v153, v20, vcc
	v_cmp_lt_i32_e32 vcc, 8, v0
	s_nop 1
	v_cndmask_b32_e32 v8, v153, v21, vcc
	v_cmp_lt_i32_e32 vcc, 9, v0
	s_nop 1
	v_cndmask_b32_e32 v9, v153, v22, vcc
	v_cmp_lt_i32_e32 vcc, 10, v0
	s_waitcnt lgkmcnt(1)
	v_mfma_f32_32x32x16_bf16 v[96:111], v[242:245], v[116:119], v[96:111]
	v_add_u32_e32 v246, s16, v166
	ds_read_b128 v[242:245], v246
	s_nop 1
	v_cndmask_b32_e32 v10, v153, v23, vcc
	v_cmp_lt_i32_e32 vcc, 15, v0
	s_nop 1
	v_cndmask_b32_e32 v11, v153, v24, vcc
	v_cmp_lt_i32_e32 vcc, 16, v0
	s_nop 1
	v_cndmask_b32_e32 v12, v153, v25, vcc
	v_cmp_lt_i32_e32 vcc, 17, v0
	s_nop 1
	v_cndmask_b32_e32 v13, v153, v26, vcc
	v_cmp_lt_i32_e32 vcc, 18, v0
	s_waitcnt lgkmcnt(1)
	v_mfma_f32_32x32x16_bf16 v[96:111], v[238:241], v[120:123], v[96:111]
	v_add_u32_e32 v246, s16, v167
	ds_read_b128 v[238:241], v246
	s_nop 1
	v_cndmask_b32_e32 v14, v153, v27, vcc
	v_cmp_lt_i32_e32 vcc, 23, v0
	s_nop 1
	v_cndmask_b32_e32 v15, v153, v28, vcc
	v_cmp_lt_i32_e32 vcc, 24, v0
	s_nop 1
	v_cndmask_b32_e32 v182, v153, v29, vcc
	v_cmp_lt_i32_e32 vcc, 25, v0
	s_nop 1
	v_cndmask_b32_e32 v183, v153, v30, vcc
	v_cmp_lt_i32_e32 vcc, 26, v0
	s_waitcnt lgkmcnt(1)
	v_mfma_f32_32x32x16_bf16 v[96:111], v[242:245], v[124:127], v[96:111]
	v_add_u32_e32 v246, s16, v168
	ds_read_b128 v[242:245], v246
	v_max_f32_e32 v0, v4, v4
	v_max_f32_e32 v0, v2, v0
	v_max3_f32 v0, v0, v5, v6
	v_max3_f32 v0, v0, v7, v8
	v_max3_f32 v0, v0, v9, v10
	v_max3_f32 v0, v0, v11, v12
	v_max3_f32 v0, v0, v13, v14
	v_cndmask_b32_e32 v184, v153, v31, vcc
	v_max3_f32 v0, v0, v15, v182
	v_max3_f32 v0, v0, v183, v184
	v_mov_b32_e32 v2, v0
	s_nop 1
	v_permlane32_swap_b32_e32 v0, v2
	s_waitcnt lgkmcnt(1)
	v_mfma_f32_32x32x16_bf16 v[96:111], v[238:241], v[128:131], v[96:111]
	v_add_u32_e32 v246, s16, v169
	ds_read_b128 v[238:241], v246
	v_max_f32_e32 v2, v2, v2
	v_max_f32_e32 v0, v0, v0
	v_max_f32_e32 v0, v0, v2
	v_mul_f32_e32 v0, 0x3e0293ee, v0
	v_add_f32_e32 v2, 0x41000000, v181
	v_cmp_gt_f32_e32 vcc, v0, v2
	s_nop 1
	v_cndmask_b32_e32 v2, v181, v0, vcc
	v_max_f32_e32 v0, v2, v2
	v_max_f32_e32 v185, 0xe0ad78ec, v0
	v_fma_f32 v0, v3, s52, -v185
	v_exp_f32_e32 v0, v0
	s_waitcnt lgkmcnt(1)
	v_mfma_f32_32x32x16_bf16 v[96:111], v[242:245], v[132:135], v[96:111]
	v_add_u32_e32 v246, s16, v170
	ds_read_b128 v[242:245], v246
	v_fma_f32 v3, v4, s52, -v185
	v_exp_f32_e32 v3, v3
	v_fma_f32 v4, v5, s52, -v185
	v_exp_f32_e32 v4, v4
	v_fma_f32 v5, v6, s52, -v185
	v_exp_f32_e32 v5, v5
	v_add_f32_e32 v6, 0, v0
	v_add_f32_e32 v6, v3, v6
	v_add_f32_e32 v6, v4, v6
	v_add_f32_e32 v186, v5, v6
	v_fma_f32 v6, v7, s52, -v185
	v_exp_f32_e32 v6, v6
	s_waitcnt lgkmcnt(1)
	v_mfma_f32_32x32x16_bf16 v[96:111], v[238:241], v[136:139], v[96:111]
	v_fma_f32 v7, v8, s52, -v185
	v_exp_f32_e32 v7, v7
	v_fma_f32 v8, v9, s52, -v185
	v_exp_f32_e32 v8, v8
	v_fma_f32 v9, v10, s52, -v185
	v_exp_f32_e32 v9, v9
	v_add_f32_e32 v10, v6, v186
	v_add_f32_e32 v10, v7, v10
	v_add_f32_e32 v10, v8, v10
	v_add_f32_e32 v186, v9, v10
	v_fma_f32 v10, v11, s52, -v185
	v_exp_f32_e32 v10, v10
	s_waitcnt lgkmcnt(0)
	v_mfma_f32_32x32x16_bf16 v[16:31], v[242:245], v[140:143], v[96:111]
	v_fma_f32 v11, v12, s52, -v185
	v_exp_f32_e32 v11, v11
	v_fma_f32 v12, v13, s52, -v185
	v_exp_f32_e32 v12, v12
	v_fma_f32 v13, v14, s52, -v185
	v_exp_f32_e32 v13, v13
	v_add_f32_e32 v14, v10, v186
	v_add_f32_e32 v14, v11, v14
	v_add_f32_e32 v14, v12, v14
	v_add_f32_e32 v186, v13, v14
	v_fma_f32 v14, v15, s52, -v185
	v_exp_f32_e32 v14, v14
	v_fma_f32 v15, v182, s52, -v185
	v_exp_f32_e32 v15, v15
	v_fma_f32 v182, v183, s52, -v185
	v_exp_f32_e32 v182, v182
	v_fma_f32 v183, v184, s52, -v185
	v_exp_f32_e32 v183, v183
	v_add_f32_e32 v184, v14, v186
	v_add_f32_e32 v184, v15, v184
	v_add_f32_e32 v184, v182, v184
	v_add_f32_e32 v184, v183, v184
	v_mov_b32_e32 v185, v184
	s_nop 1
	v_permlane32_swap_b32_e32 v184, v185
	s_cbranch_vccz .Lfs_cmp_427
	v_sub_f32_e32 v181, v181, v2
	v_exp_f32_e32 v186, v181
	s_nop 0
	v_mul_f32_e32 v179, v179, v186
	v_pk_mul_f32 v[94:95], v[94:95], v[186:187] op_sel_hi:[1,0]
	v_pk_mul_f32 v[92:93], v[92:93], v[186:187] op_sel_hi:[1,0]
	v_pk_mul_f32 v[90:91], v[90:91], v[186:187] op_sel_hi:[1,0]
	v_pk_mul_f32 v[88:89], v[88:89], v[186:187] op_sel_hi:[1,0]
	v_pk_mul_f32 v[86:87], v[86:87], v[186:187] op_sel_hi:[1,0]
	v_pk_mul_f32 v[84:85], v[84:85], v[186:187] op_sel_hi:[1,0]
	v_pk_mul_f32 v[82:83], v[82:83], v[186:187] op_sel_hi:[1,0]
	v_pk_mul_f32 v[80:81], v[80:81], v[186:187] op_sel_hi:[1,0]
	v_pk_mul_f32 v[78:79], v[78:79], v[186:187] op_sel_hi:[1,0]
	v_pk_mul_f32 v[76:77], v[76:77], v[186:187] op_sel_hi:[1,0]
	v_pk_mul_f32 v[74:75], v[74:75], v[186:187] op_sel_hi:[1,0]
	v_pk_mul_f32 v[72:73], v[72:73], v[186:187] op_sel_hi:[1,0]
	v_pk_mul_f32 v[70:71], v[70:71], v[186:187] op_sel_hi:[1,0]
	v_pk_mul_f32 v[68:69], v[68:69], v[186:187] op_sel_hi:[1,0]
	v_pk_mul_f32 v[66:67], v[66:67], v[186:187] op_sel_hi:[1,0]
	v_pk_mul_f32 v[64:65], v[64:65], v[186:187] op_sel_hi:[1,0]
	v_pk_mul_f32 v[62:63], v[62:63], v[186:187] op_sel_hi:[1,0]
	v_pk_mul_f32 v[60:61], v[60:61], v[186:187] op_sel_hi:[1,0]
	v_pk_mul_f32 v[58:59], v[58:59], v[186:187] op_sel_hi:[1,0]
	v_pk_mul_f32 v[56:57], v[56:57], v[186:187] op_sel_hi:[1,0]
	v_pk_mul_f32 v[54:55], v[54:55], v[186:187] op_sel_hi:[1,0]
	v_pk_mul_f32 v[52:53], v[52:53], v[186:187] op_sel_hi:[1,0]
	v_pk_mul_f32 v[50:51], v[50:51], v[186:187] op_sel_hi:[1,0]
	v_pk_mul_f32 v[48:49], v[48:49], v[186:187] op_sel_hi:[1,0]
	v_pk_mul_f32 v[46:47], v[46:47], v[186:187] op_sel_hi:[1,0]
	v_pk_mul_f32 v[44:45], v[44:45], v[186:187] op_sel_hi:[1,0]
	v_pk_mul_f32 v[42:43], v[42:43], v[186:187] op_sel_hi:[1,0]
	v_pk_mul_f32 v[40:41], v[40:41], v[186:187] op_sel_hi:[1,0]
	v_pk_mul_f32 v[38:39], v[38:39], v[186:187] op_sel_hi:[1,0]
	v_pk_mul_f32 v[36:37], v[36:37], v[186:187] op_sel_hi:[1,0]
	v_pk_mul_f32 v[34:35], v[34:35], v[186:187] op_sel_hi:[1,0]
	v_pk_mul_f32 v[32:33], v[32:33], v[186:187] op_sel_hi:[1,0]
; #define LAS __attribute__((address_space(3)))
; DI float xh_sum(float x) { const unsigned u = __float_as_uint(x); const auto r = __builtin_amdgcn_permlane32_swap(u, u, false, false); return __uint_as_float(r[0]) + __uint_as_float(r[1]); }
; #define MFMA32(a, b, c) __builtin_amdgcn_mfma_f32_32x32x16_bf16((a), (b), (c), 0, 0, 0)
; DI bf16x8 cat44(s16x4 a, s16x4 b) { return __builtin_shufflevector(a, b, 0, 1, 2, 3, 4, 5, 6, 7); }
; template <int MODE>
; DI void co_finish(f32x16 S, LAS unsigned char* st, int key_base, AttnState& as, int tq, bool rowsel, int vb_in, int hh) {
;     ...
;     for (int i = 0; i < 16; ++i) { const float p = __builtin_amdgcn_exp2f(__builtin_fmaf(S[i], SM_SCALE, muse)); S[i] = p; ps += p; }
;     ps = xh_sum(ps);
;     if (__builtin_amdgcn_ballot_w64(need) != 0ull) {
;         const float alpha = __builtin_amdgcn_exp2f(as.m - mnew);
;         as.l *= alpha;
; #pragma unroll
;         for (int dt = 0; dt < 4; ++dt)
; #pragma unroll
;             for (int i = 0; i < 16; ++i) as.acc[dt][i] *= alpha;
;     }
;     as.l += ps; as.m = mnew;
;     const bf16x8 p0 = pack8(S, 0), p1 = pack8(S, 1);
;     __builtin_amdgcn_s_setprio(1);
; #pragma unroll
;     for (int dt = 0; dt < 4; ++dt) {
;         LAS unsigned char* vp = st + 2048 * dt;
;         const bf16x8 a0 = cat44(*(const LAS s16x4*)(vp + (vb ^ 0)), *(const LAS s16x4*)(vp + (vb ^ 16))), a1 = cat44(*(const LAS s16x4*)(vp + (vb ^ 32)), *(const LAS s16x4*)(vp + (vb ^ 48)));
;         as.acc[dt] = MFMA32(a0, p0, as.acc[dt]); as.acc[dt] = MFMA32(a1, p1, as.acc[dt]);
;     }
;     __builtin_amdgcn_s_setprio(0);
.Lfs_cmp_427:
	v_add_f32_e32 v181, v184, v185
	v_add_f32_e32 v179, v181, v179
	v_cvt_pk_bf16_f32 v184, v0, v3
	v_cvt_pk_bf16_f32 v185, v4, v5
	v_cvt_pk_bf16_f32 v186, v6, v7
	v_cvt_pk_bf16_f32 v187, v8, v9
	v_cvt_pk_bf16_f32 v4, v10, v11
	v_cvt_pk_bf16_f32 v5, v12, v13
	v_cvt_pk_bf16_f32 v6, v14, v15
	v_cvt_pk_bf16_f32 v7, v182, v183
	v_add_u32_e32 v0, s62, v156
	v_add_u32_e32 v3, s62, v171
	ds_read2st64_b64 v[8:11], v0 offset0:16 offset1:20
	ds_read2st64_b64 v[12:15], v3 offset0:16 offset1:20
	v_add_u32_e32 v181, s62, v172
	v_add_u32_e32 v182, s62, v173
	ds_read2st64_b64 v[192:195], v181 offset0:16 offset1:20
	ds_read2st64_b64 v[196:199], v182 offset0:16 offset1:20
	s_waitcnt lgkmcnt(0)
	v_mov_b32_e32 v190, v12
	v_mov_b32_e32 v191, v13
	v_mov_b32_e32 v12, v10
	v_mov_b32_e32 v13, v11
	v_mov_b32_e32 v188, v8
	v_mov_b32_e32 v189, v9
	v_mfma_f32_32x32x16_bf16 v[64:79], v[12:15], v[184:187], v[64:79]
	ds_read2st64_b64 v[8:11], v0 offset0:24 offset1:28
	ds_read2st64_b64 v[12:15], v3 offset0:24 offset1:28
	v_mov_b32_e32 v202, v196
	v_mov_b32_e32 v203, v197
	v_mov_b32_e32 v196, v194
	v_mov_b32_e32 v197, v195
	v_mov_b32_e32 v200, v192
	v_mov_b32_e32 v201, v193
	v_mfma_f32_32x32x16_bf16 v[80:95], v[188:191], v[184:187], v[80:95]
	s_waitcnt lgkmcnt(0)
	v_mov_b32_e32 v188, v8
	v_mov_b32_e32 v189, v9
	v_mov_b32_e32 v190, v12
	v_mov_b32_e32 v191, v13
	v_mov_b32_e32 v12, v10
	v_mov_b32_e32 v13, v11
	ds_read2st64_b64 v[192:195], v181 offset0:24 offset1:28
	v_mfma_f32_32x32x16_bf16 v[64:79], v[196:199], v[4:7], v[64:79]
	ds_read2st64_b64 v[196:199], v182 offset0:24 offset1:28
	v_mfma_f32_32x32x16_bf16 v[48:63], v[188:191], v[184:187], v[48:63]
	v_mfma_f32_32x32x16_bf16 v[32:47], v[12:15], v[184:187], v[32:47]
	v_mfma_f32_32x32x16_bf16 v[80:95], v[200:203], v[4:7], v[80:95]
	s_waitcnt lgkmcnt(0)
	v_mov_b32_e32 v200, v192
	v_mov_b32_e32 v201, v193
	v_mov_b32_e32 v202, v196
	v_mov_b32_e32 v203, v197
	v_mov_b32_e32 v196, v194
	v_mov_b32_e32 v197, v195
	v_mfma_f32_32x32x16_bf16 v[48:63], v[200:203], v[4:7], v[48:63]
	s_nop 0
	v_mfma_f32_32x32x16_bf16 v[32:47], v[196:199], v[4:7], v[32:47]
	s_mov_b64 s[26:27], -1
	s_mov_b32 s62, s16
	s_mov_b32 s64, s76
	s_branch .LBB0_430
